# speedup vs baseline: 1.0126x; 1.0072x over previous
; __device__ void phase_prep(const Params& p) {
;     ...
;       const float* w1 = p.in[17]; const float* b1 = p.in[18]; const float* w2 = p.in[19]; const float* b2 = p.in[20];
;       float fr = p.in[22][lane];
;       float a1 = b1[lane];
;       for (int k = 0; k < 33; ++k) a1 += __shfl(feat, k) * w1[k * 64 + lane];
;       float h1 = sinf(fr * a1);
.LBB0_625:
	global_load_dword v100, v[4:5], off offset:-2560
	global_load_dword v101, v[4:5], off offset:-2304
	global_load_dword v102, v[4:5], off offset:-2048
	global_load_dword v103, v[4:5], off offset:-1792
	global_load_dword v104, v[4:5], off offset:-1536
	global_load_dword v105, v[4:5], off offset:-1280
	global_load_dword v106, v[4:5], off offset:-1024
	global_load_dword v107, v[4:5], off offset:-768
	global_load_dword v108, v[4:5], off offset:-512
	global_load_dword v109, v[4:5], off offset:-256
	global_load_dword v110, v[4:5], off
	v_add_u32_e32 v8, s12, v6
	ds_bpermute_b32 v120, v8, v0
	ds_bpermute_b32 v121, v8, v0 offset:4
	ds_bpermute_b32 v122, v8, v0 offset:8
	ds_bpermute_b32 v123, v8, v0 offset:12
	ds_bpermute_b32 v124, v8, v0 offset:16
	ds_bpermute_b32 v125, v8, v0 offset:20
	ds_bpermute_b32 v126, v8, v0 offset:24
	ds_bpermute_b32 v127, v8, v0 offset:28
	ds_bpermute_b32 v128, v8, v0 offset:32
	ds_bpermute_b32 v129, v8, v0 offset:36
	ds_bpermute_b32 v130, v8, v0 offset:40
	s_add_i32 s12, s12, 44
	s_mov_b64 s[16:17], 0xb00
	s_cmpk_eq_i32 s12, 0x84
	v_lshl_add_u64 v[4:5], v[4:5], 0, s[16:17]
	s_waitcnt vmcnt(0) lgkmcnt(0)
	v_fmac_f32_e32 v7, v100, v120
	v_fmac_f32_e32 v7, v101, v121
	v_fmac_f32_e32 v7, v102, v122
	v_fmac_f32_e32 v7, v103, v123
	v_fmac_f32_e32 v7, v104, v124
	v_fmac_f32_e32 v7, v105, v125
	v_fmac_f32_e32 v7, v106, v126
	v_fmac_f32_e32 v7, v107, v127
	v_fmac_f32_e32 v7, v108, v128
	v_fmac_f32_e32 v7, v109, v129
	v_fmac_f32_e32 v7, v110, v130
	s_cbranch_scc0 .LBB0_625
	v_mul_f32_e32 v4, v3, v7
	s_brev_b32 s12, 18
	v_and_b32_e32 v5, 0x7fffffff, v4
	v_cmp_nlt_f32_e64 s[12:13], |v4|, s12
	s_and_saveexec_b64 s[16:17], s[12:13]
	s_xor_b64 s[76:77], exec, s[16:17]
	s_cbranch_execz .LBB0_628
	v_lshrrev_b32_e32 v0, 23, v5
	v_add_u32_e32 v0, 0xffffff88, v0
	v_cmp_lt_u32_e32 vcc, 63, v0
	s_mov_b32 s18, 0xfe5163ab
	s_nop 0
	v_cndmask_b32_e32 v7, 0, v215, vcc
	v_add_u32_e32 v0, v7, v0
	v_cmp_lt_u32_e64 s[12:13], 31, v0
	s_nop 1
	v_cndmask_b32_e64 v7, 0, v217, s[12:13]
	v_add_u32_e32 v0, v7, v0
	v_cmp_lt_u32_e64 s[16:17], 31, v0
	s_nop 1
	v_cndmask_b32_e64 v7, 0, v217, s[16:17]
	v_add_u32_e32 v7, v7, v0
	v_and_b32_e32 v0, 0x7fffff, v5
	v_or_b32_e32 v20, 0x800000, v0
	v_mad_u64_u32 v[8:9], s[18:19], v20, s18, 0
	v_mov_b32_e32 v0, v9
	s_mov_b32 s18, 0x3c439041
	v_mad_u64_u32 v[10:11], s[18:19], v20, s18, v[0:1]
	v_mov_b32_e32 v0, v11
	s_mov_b32 s18, 0xdb629599
	v_mad_u64_u32 v[12:13], s[18:19], v20, s18, v[0:1]
	v_mov_b32_e32 v0, v13
	s_mov_b32 s18, 0xf534ddc0
	v_mad_u64_u32 v[14:15], s[18:19], v20, s18, v[0:1]
	v_mov_b32_e32 v0, v15
	s_mov_b32 s18, 0xfc2757d1
	v_mad_u64_u32 v[16:17], s[18:19], v20, s18, v[0:1]
	v_mov_b32_e32 v0, v17
	s_mov_b32 s18, 0x4e441529
	v_mad_u64_u32 v[18:19], s[18:19], v20, s18, v[0:1]
	v_mov_b32_e32 v0, v19
	s_mov_b32 s18, 0xa2f9836e
	v_mad_u64_u32 v[20:21], s[18:19], v20, s18, v[0:1]
	v_cndmask_b32_e32 v9, v18, v14, vcc
	v_cndmask_b32_e32 v0, v20, v16, vcc
	v_cndmask_b32_e32 v13, v21, v18, vcc
	v_cndmask_b32_e64 v11, v0, v9, s[12:13]
	v_cndmask_b32_e64 v0, v13, v0, s[12:13]
	v_cndmask_b32_e32 v13, v16, v12, vcc
	v_cndmask_b32_e64 v9, v9, v13, s[12:13]
	v_sub_u32_e32 v15, 32, v7
	v_cmp_eq_u32_e64 s[18:19], 0, v7
	v_cndmask_b32_e32 v7, v14, v10, vcc
	v_cndmask_b32_e64 v0, v0, v11, s[16:17]
	v_cndmask_b32_e64 v11, v11, v9, s[16:17]
	v_cndmask_b32_e64 v10, v13, v7, s[12:13]
	v_alignbit_b32 v16, v0, v11, v15
	v_cndmask_b32_e64 v9, v9, v10, s[16:17]
	v_cndmask_b32_e64 v0, v16, v0, s[18:19]
	v_alignbit_b32 v13, v11, v9, v15
	v_cndmask_b32_e32 v8, v12, v8, vcc
	v_cndmask_b32_e64 v11, v13, v11, s[18:19]
	v_bfe_u32 v16, v0, 29, 1
	v_cndmask_b32_e64 v7, v7, v8, s[12:13]
	v_alignbit_b32 v13, v0, v11, 30
	v_sub_u32_e32 v17, 0, v16
	v_cndmask_b32_e64 v7, v10, v7, s[16:17]
	v_xor_b32_e32 v13, v13, v17
	v_alignbit_b32 v8, v9, v7, v15
	v_cndmask_b32_e64 v8, v8, v9, s[18:19]
	v_ffbh_u32_e32 v10, v13
	v_alignbit_b32 v9, v11, v8, 30
	v_min_u32_e32 v10, 32, v10
	v_alignbit_b32 v7, v8, v7, 30
	v_xor_b32_e32 v9, v9, v17
	v_sub_u32_e32 v11, 31, v10
	v_xor_b32_e32 v7, v7, v17
	v_alignbit_b32 v12, v13, v9, v11
	v_alignbit_b32 v7, v9, v7, v11
	v_alignbit_b32 v8, v12, v7, 9
	v_ffbh_u32_e32 v9, v8
	v_min_u32_e32 v9, 32, v9
	v_lshrrev_b32_e32 v14, 29, v0
	v_not_b32_e32 v11, v9
	v_alignbit_b32 v7, v8, v7, v11
	v_lshlrev_b32_e32 v8, 31, v14
	v_or_b32_e32 v11, 0x33000000, v8
	v_add_lshl_u32 v9, v9, v10, 23
	v_lshrrev_b32_e32 v7, 9, v7
	v_sub_u32_e32 v9, v11, v9
	v_or_b32_e32 v8, 0.5, v8
	v_lshlrev_b32_e32 v10, 23, v10
	v_or_b32_e32 v7, v9, v7
	v_lshrrev_b32_e32 v9, 9, v12
	v_sub_u32_e32 v8, v8, v10
	v_or_b32_e32 v8, v9, v8
	v_mul_f32_e32 v9, 0x3fc90fda, v8
	s_mov_b32 s12, 0x3fc90fda
	v_fma_f32 v10, v8, s12, -v9
	v_fmac_f32_e32 v10, 0x33a22168, v8
	v_fmac_f32_e32 v10, 0x3fc90fda, v7
	v_lshrrev_b32_e32 v0, 30, v0
	v_add_f32_e32 v7, v9, v10
	v_add_u32_e32 v0, v16, v0

; __device__ void phase_prep(const Params& p) {
;     ...
;       float a2 = b2[lane];
;       for (int k = 0; k < 64; ++k) a2 += __shfl(h1, k) * w2[k * 64 + lane];
;       float h2 = sinf(fr * a2);
.LBB0_631:
	global_load_dword v100, v[4:5], off offset:-1792
	global_load_dword v101, v[4:5], off offset:-1536
	global_load_dword v102, v[4:5], off offset:-1280
	global_load_dword v103, v[4:5], off offset:-1024
	global_load_dword v104, v[4:5], off offset:-768
	global_load_dword v105, v[4:5], off offset:-512
	global_load_dword v106, v[4:5], off offset:-256
	global_load_dword v107, v[4:5], off
	v_add_u32_e32 v8, s12, v6
	ds_bpermute_b32 v120, v8, v7
	ds_bpermute_b32 v121, v8, v7 offset:4
	ds_bpermute_b32 v122, v8, v7 offset:8
	ds_bpermute_b32 v123, v8, v7 offset:12
	ds_bpermute_b32 v124, v8, v7 offset:16
	ds_bpermute_b32 v125, v8, v7 offset:20
	ds_bpermute_b32 v126, v8, v7 offset:24
	ds_bpermute_b32 v127, v8, v7 offset:28
	s_add_i32 s12, s12, 32
	s_mov_b64 s[16:17], 0x800
	s_cmpk_eq_i32 s12, 0x100
	v_lshl_add_u64 v[4:5], v[4:5], 0, s[16:17]
	s_waitcnt vmcnt(0) lgkmcnt(0)
	v_fmac_f32_e32 v0, v100, v120
	v_fmac_f32_e32 v0, v101, v121
	v_fmac_f32_e32 v0, v102, v122
	v_fmac_f32_e32 v0, v103, v123
	v_fmac_f32_e32 v0, v104, v124
	v_fmac_f32_e32 v0, v105, v125
	v_fmac_f32_e32 v0, v106, v126
	v_fmac_f32_e32 v0, v107, v127
	s_cbranch_scc0 .LBB0_631
	v_mul_f32_e32 v3, v3, v0
	s_brev_b32 s12, 18
	v_and_b32_e32 v4, 0x7fffffff, v3
	v_cmp_nlt_f32_e64 s[12:13], |v3|, s12
	s_and_saveexec_b64 s[16:17], s[12:13]
	s_xor_b64 s[76:77], exec, s[16:17]
	s_cbranch_execz .LBB0_634
	v_lshrrev_b32_e32 v0, 23, v4
	v_add_u32_e32 v0, 0xffffff88, v0
	v_cmp_lt_u32_e32 vcc, 63, v0
	s_mov_b32 s18, 0xfe5163ab
	s_nop 0
	v_cndmask_b32_e32 v5, 0, v215, vcc
	v_add_u32_e32 v0, v5, v0
	v_cmp_lt_u32_e64 s[12:13], 31, v0
	s_nop 1
	v_cndmask_b32_e64 v5, 0, v217, s[12:13]
	v_add_u32_e32 v0, v5, v0
	v_cmp_lt_u32_e64 s[16:17], 31, v0
	s_nop 1
	v_cndmask_b32_e64 v5, 0, v217, s[16:17]
	v_add_u32_e32 v5, v5, v0
	v_and_b32_e32 v0, 0x7fffff, v4
	v_or_b32_e32 v18, 0x800000, v0
	v_mad_u64_u32 v[6:7], s[18:19], v18, s18, 0
	v_mov_b32_e32 v0, v7
	s_mov_b32 s18, 0x3c439041
	v_mad_u64_u32 v[8:9], s[18:19], v18, s18, v[0:1]
	v_mov_b32_e32 v0, v9
	s_mov_b32 s18, 0xdb629599
	v_mad_u64_u32 v[10:11], s[18:19], v18, s18, v[0:1]
	v_mov_b32_e32 v0, v11
	s_mov_b32 s18, 0xf534ddc0
	v_mad_u64_u32 v[12:13], s[18:19], v18, s18, v[0:1]
	v_mov_b32_e32 v0, v13
	s_mov_b32 s18, 0xfc2757d1
	v_mad_u64_u32 v[14:15], s[18:19], v18, s18, v[0:1]
	v_mov_b32_e32 v0, v15
	s_mov_b32 s18, 0x4e441529
	v_mad_u64_u32 v[16:17], s[18:19], v18, s18, v[0:1]
	v_mov_b32_e32 v0, v17
	s_mov_b32 s18, 0xa2f9836e
	v_mad_u64_u32 v[18:19], s[18:19], v18, s18, v[0:1]
	v_cndmask_b32_e32 v7, v16, v12, vcc
	v_cndmask_b32_e32 v0, v18, v14, vcc
	v_cndmask_b32_e32 v11, v19, v16, vcc
	v_cndmask_b32_e64 v9, v0, v7, s[12:13]
	v_cndmask_b32_e64 v0, v11, v0, s[12:13]
	v_cndmask_b32_e32 v11, v14, v10, vcc
	v_cndmask_b32_e64 v7, v7, v11, s[12:13]
	v_sub_u32_e32 v13, 32, v5
	v_cmp_eq_u32_e64 s[18:19], 0, v5
	v_cndmask_b32_e32 v5, v12, v8, vcc
	v_cndmask_b32_e64 v0, v0, v9, s[16:17]
	v_cndmask_b32_e64 v9, v9, v7, s[16:17]
	v_cndmask_b32_e64 v8, v11, v5, s[12:13]
	v_alignbit_b32 v14, v0, v9, v13
	v_cndmask_b32_e64 v7, v7, v8, s[16:17]
	v_cndmask_b32_e64 v0, v14, v0, s[18:19]
	v_alignbit_b32 v11, v9, v7, v13
	v_cndmask_b32_e32 v6, v10, v6, vcc
	v_cndmask_b32_e64 v9, v11, v9, s[18:19]
	v_bfe_u32 v14, v0, 29, 1
	v_cndmask_b32_e64 v5, v5, v6, s[12:13]
	v_alignbit_b32 v11, v0, v9, 30
	v_sub_u32_e32 v15, 0, v14
	v_cndmask_b32_e64 v5, v8, v5, s[16:17]
	v_xor_b32_e32 v11, v11, v15
	v_alignbit_b32 v6, v7, v5, v13
	v_cndmask_b32_e64 v6, v6, v7, s[18:19]
	v_ffbh_u32_e32 v8, v11
	v_alignbit_b32 v7, v9, v6, 30
	v_min_u32_e32 v8, 32, v8
	v_alignbit_b32 v5, v6, v5, 30
	v_xor_b32_e32 v7, v7, v15
	v_sub_u32_e32 v9, 31, v8
	v_xor_b32_e32 v5, v5, v15
	v_alignbit_b32 v10, v11, v7, v9
	v_alignbit_b32 v5, v7, v5, v9
	v_alignbit_b32 v6, v10, v5, 9
	v_ffbh_u32_e32 v7, v6
	v_min_u32_e32 v7, 32, v7
	v_lshrrev_b32_e32 v12, 29, v0
	v_not_b32_e32 v9, v7
	v_alignbit_b32 v5, v6, v5, v9
	v_lshlrev_b32_e32 v6, 31, v12
	v_or_b32_e32 v9, 0x33000000, v6
	v_add_lshl_u32 v7, v7, v8, 23
	v_lshrrev_b32_e32 v5, 9, v5
	v_sub_u32_e32 v7, v9, v7
	v_or_b32_e32 v6, 0.5, v6
	v_lshlrev_b32_e32 v8, 23, v8
	v_or_b32_e32 v5, v7, v5
	v_lshrrev_b32_e32 v7, 9, v10
	v_sub_u32_e32 v6, v6, v8
	v_or_b32_e32 v6, v7, v6
	v_mul_f32_e32 v7, 0x3fc90fda, v6
	s_mov_b32 s12, 0x3fc90fda
	v_fma_f32 v8, v6, s12, -v7
	v_fmac_f32_e32 v8, 0x33a22168, v6
	v_fmac_f32_e32 v8, 0x3fc90fda, v5
	v_lshrrev_b32_e32 v0, 30, v0
	v_add_f32_e32 v5, v7, v8
	v_add_u32_e32 v0, v14, v0
